# scan loop: LDS operands prefetched two steps ahead (3 register sets), y dot of step t-1 interleaved with d dot of step t
# baseline (speedup 1.0000x reference)
; #define LAS __attribute__((address_space(3)))
; __device__ __forceinline__ float sum16(float x) { x = dpp_add<0xB1>(x); x = dpp_add<0x4E>(x); x = dpp_add<0x141>(x); x = dpp_add<0x140>(x); return x; }
; __device__ __forceinline__ void scan_step(f32x4& S, const ScanOps& o, LAS float* yp) {
;     f32x2 S0 = {S[0], S[1]}, S1 = {S[2], S[3]};
;     const f32x2 k0 = {o.kk[0], o.kk[1]}, k1 = {o.kk[2], o.kk[3]};
;     f32x2 t = S0 * k0; t = S1 * k1 + t;
;     const float sa = -sum16(t[0] + t[1]);
;     const f32x2 sav = {sa, sa}, vv = {o.v, o.v};
;     const f32x2 a0 = {o.ka[0], o.ka[1]}, a1 = {o.ka[2], o.ka[3]}, p0 = {o.kp[0], o.kp[1]}, p1 = {o.kp[2], o.kp[3]}, w0 = {o.w[0], o.w[1]}, w1 = {o.w[2], o.w[3]};
;     f32x2 u0 = a0 * sav; u0 = p0 * vv + u0; S0 = S0 * w0 + u0;
;     f32x2 u1 = a1 * sav; u1 = p1 * vv + u1; S1 = S1 * w1 + u1;
;     const f32x2 r0 = {o.rr[0], o.rr[1]}, r1 = {o.rr[2], o.rr[3]};
;     f32x2 y = S0 * r0; y = S1 * r1 + y;
;     *yp = y[0] + y[1];
;     S = (f32x4){S0[0], S0[1], S1[0], S1[1]};
; }
; __device__ __forceinline__ void scan_unit(const Ctx& p, int chain, int rq, LAS unsigned char* lds) {
;     ...
;             for (int t = 0; t < SCH; t += 2) {
;                 scan_load(ob, OP, VP, t + 1);
;                 oa.v = vv[0]; ob.v = vv[1];
;                 scan_step(S, oa, Y + t * 256);
;                 scan_load(oa, OP, VP, (t + 2) & (SCH - 1));
;                 vv = *(const LAS f32x2*)(VP + ((t + 2) & (SCH - 1)));
;                 scan_step(S, ob, Y + (t + 1) * 256);
;             }
.LBB0_1714:
	s_and_b32 s12, s10, 1
	s_mulk_i32 s12, 0x5400
	s_lshl_b32 s13, s10, 14
	v_lshl_add_u32 v31, v26, 2, s12
	s_and_b32 s13, s13, 0x4000
	v_lshl_add_u32 v32, v28, 2, s12
	v_add_u32_e32 v33, s13, v29
	s_waitcnt lgkmcnt(0)
	s_barrier
	ds_read_b128 v[60:63], v31 offset:256
	ds_read_b128 v[64:67], v31 offset:768
	ds_read_b128 v[40:43], v32 offset:20480
	ds_read_b128 v[68:71], v31 offset:0
	ds_read_b128 v[72:75], v31 offset:512
	ds_read_b128 v[76:79], v31 offset:1024
	ds_read_b128 v[80:83], v31 offset:1536
	ds_read_b128 v[84:87], v31 offset:2048
	ds_read_b128 v[88:91], v31 offset:1280
	ds_read_b128 v[92:95], v31 offset:1792
	ds_read_b128 v[96:99], v31 offset:2304
	ds_read_b128 v[44:47], v32 offset:20496
	ds_read_b128 v[48:51], v32 offset:20512
	ds_read_b128 v[52:55], v32 offset:20528
	s_waitcnt lgkmcnt(13)
	v_mul_f32_e32 v100, v0, v60
	v_fmac_f32_e32 v100, v1, v61
	v_fmac_f32_e32 v100, v2, v62
	v_fmac_f32_e32 v100, v3, v63
	s_waitcnt lgkmcnt(11)
	v_mul_f32_e32 v104, v64, v40
	v_mul_f32_e32 v105, v65, v40
	v_add_f32_dpp v100, v100, v100 quad_perm:[1,0,3,2] row_mask:0xf bank_mask:0xf bound_ctrl:1
	v_mul_f32_e32 v106, v66, v40
	v_mul_f32_e32 v107, v67, v40
	v_add_f32_dpp v100, v100, v100 quad_perm:[2,3,0,1] row_mask:0xf bank_mask:0xf bound_ctrl:1
	s_waitcnt lgkmcnt(10)
	v_fmac_f32_e32 v104, v0, v68
	v_fmac_f32_e32 v105, v1, v69
	v_add_f32_dpp v100, v100, v100 row_half_mirror row_mask:0xf bank_mask:0xf bound_ctrl:1
	v_fmac_f32_e32 v106, v2, v70
	v_fmac_f32_e32 v107, v3, v71
	v_add_f32_dpp v100, v100, v100 row_mirror row_mask:0xf bank_mask:0xf bound_ctrl:1
	s_waitcnt lgkmcnt(9)
	v_fma_f32 v0, -v72, v100, v104
	v_fma_f32 v1, -v73, v100, v105
	v_fma_f32 v2, -v74, v100, v106
	v_fma_f32 v3, -v75, v100, v107
	ds_read_b128 v[120:123], v31 offset:2816
	ds_read_b128 v[124:127], v31 offset:3328
	ds_read_b128 v[128:131], v31 offset:2560
	ds_read_b128 v[132:135], v31 offset:3072
	ds_read_b128 v[136:139], v31 offset:3584
	s_waitcnt lgkmcnt(7)
	ds_read_b128 v[60:63], v31 offset:4096
	ds_read_b128 v[64:67], v31 offset:4608
	ds_read_b128 v[68:71], v31 offset:3840
	ds_read_b128 v[72:75], v31 offset:4352
	v_mul_f32_e32 v100, v0, v80
	v_mul_f32_e32 v101, v0, v76
	v_fmac_f32_e32 v100, v1, v81
	v_fmac_f32_e32 v101, v1, v77
	v_fmac_f32_e32 v100, v2, v82
	v_fmac_f32_e32 v101, v2, v78
	v_fmac_f32_e32 v100, v3, v83
	v_fmac_f32_e32 v101, v3, v79
	ds_write_b32 v33, v101 offset:0
	ds_read_b128 v[76:79], v31 offset:4864
	v_mul_f32_e32 v104, v84, v41
	v_mul_f32_e32 v105, v85, v41
	v_add_f32_dpp v100, v100, v100 quad_perm:[1,0,3,2] row_mask:0xf bank_mask:0xf bound_ctrl:1
	v_mul_f32_e32 v106, v86, v41
	v_mul_f32_e32 v107, v87, v41
	v_add_f32_dpp v100, v100, v100 quad_perm:[2,3,0,1] row_mask:0xf bank_mask:0xf bound_ctrl:1
	v_fmac_f32_e32 v104, v0, v88
	v_fmac_f32_e32 v105, v1, v89
	v_add_f32_dpp v100, v100, v100 row_half_mirror row_mask:0xf bank_mask:0xf bound_ctrl:1
	v_fmac_f32_e32 v106, v2, v90
	v_fmac_f32_e32 v107, v3, v91
	v_add_f32_dpp v100, v100, v100 row_mirror row_mask:0xf bank_mask:0xf bound_ctrl:1
	v_fma_f32 v0, -v92, v100, v104
	v_fma_f32 v1, -v93, v100, v105
	v_fma_f32 v2, -v94, v100, v106
	v_fma_f32 v3, -v95, v100, v107
	s_waitcnt lgkmcnt(7)
	ds_read_b128 v[80:83], v31 offset:5376
	ds_read_b128 v[84:87], v31 offset:5888
	ds_read_b128 v[88:91], v31 offset:5120
	ds_read_b128 v[92:95], v31 offset:5632
	v_mul_f32_e32 v100, v0, v120
	v_mul_f32_e32 v101, v0, v96
	v_fmac_f32_e32 v100, v1, v121
	v_fmac_f32_e32 v101, v1, v97
	v_fmac_f32_e32 v100, v2, v122
	v_fmac_f32_e32 v101, v2, v98
	v_fmac_f32_e32 v100, v3, v123
	v_fmac_f32_e32 v101, v3, v99
	ds_write_b32 v33, v101 offset:1024
	ds_read_b128 v[96:99], v31 offset:6144
	v_mul_f32_e32 v104, v124, v42
	v_mul_f32_e32 v105, v125, v42
	v_add_f32_dpp v100, v100, v100 quad_perm:[1,0,3,2] row_mask:0xf bank_mask:0xf bound_ctrl:1
	v_mul_f32_e32 v106, v126, v42
	v_mul_f32_e32 v107, v127, v42
	v_add_f32_dpp v100, v100, v100 quad_perm:[2,3,0,1] row_mask:0xf bank_mask:0xf bound_ctrl:1
	v_fmac_f32_e32 v104, v0, v128
	v_fmac_f32_e32 v105, v1, v129
	v_add_f32_dpp v100, v100, v100 row_half_mirror row_mask:0xf bank_mask:0xf bound_ctrl:1
	v_fmac_f32_e32 v106, v2, v130
	v_fmac_f32_e32 v107, v3, v131
	v_add_f32_dpp v100, v100, v100 row_mirror row_mask:0xf bank_mask:0xf bound_ctrl:1
	v_fma_f32 v0, -v132, v100, v104
	v_fma_f32 v1, -v133, v100, v105
	v_fma_f32 v2, -v134, v100, v106
	v_fma_f32 v3, -v135, v100, v107
	s_waitcnt lgkmcnt(8)
	ds_read_b128 v[120:123], v31 offset:6656
	ds_read_b128 v[124:127], v31 offset:7168
	ds_read_b128 v[128:131], v31 offset:6400
	ds_read_b128 v[132:135], v31 offset:6912
	v_mul_f32_e32 v100, v0, v60
	v_mul_f32_e32 v101, v0, v136
	v_fmac_f32_e32 v100, v1, v61
	v_fmac_f32_e32 v101, v1, v137
	v_fmac_f32_e32 v100, v2, v62
	v_fmac_f32_e32 v101, v2, v138
	v_fmac_f32_e32 v100, v3, v63
	v_fmac_f32_e32 v101, v3, v139
	ds_write_b32 v33, v101 offset:2048
	ds_read_b128 v[136:139], v31 offset:7424
	v_mul_f32_e32 v104, v64, v43
	v_mul_f32_e32 v105, v65, v43
	v_add_f32_dpp v100, v100, v100 quad_perm:[1,0,3,2] row_mask:0xf bank_mask:0xf bound_ctrl:1
	v_mul_f32_e32 v106, v66, v43
	v_mul_f32_e32 v107, v67, v43
	v_add_f32_dpp v100, v100, v100 quad_perm:[2,3,0,1] row_mask:0xf bank_mask:0xf bound_ctrl:1
	v_fmac_f32_e32 v104, v0, v68
	v_fmac_f32_e32 v105, v1, v69
	v_add_f32_dpp v100, v100, v100 row_half_mirror row_mask:0xf bank_mask:0xf bound_ctrl:1
	v_fmac_f32_e32 v106, v2, v70
	v_fmac_f32_e32 v107, v3, v71
	v_add_f32_dpp v100, v100, v100 row_mirror row_mask:0xf bank_mask:0xf bound_ctrl:1
	v_fma_f32 v0, -v72, v100, v104
	v_fma_f32 v1, -v73, v100, v105
	v_fma_f32 v2, -v74, v100, v106
	v_fma_f32 v3, -v75, v100, v107
	s_waitcnt lgkmcnt(8)
; #define LAS __attribute__((address_space(3)))
; __device__ __forceinline__ float sum16(float x) { x = dpp_add<0xB1>(x); x = dpp_add<0x4E>(x); x = dpp_add<0x141>(x); x = dpp_add<0x140>(x); return x; }
; __device__ __forceinline__ void scan_step(f32x4& S, const ScanOps& o, LAS float* yp) {
;     f32x2 S0 = {S[0], S[1]}, S1 = {S[2], S[3]};
;     const f32x2 k0 = {o.kk[0], o.kk[1]}, k1 = {o.kk[2], o.kk[3]};
;     f32x2 t = S0 * k0; t = S1 * k1 + t;
;     const float sa = -sum16(t[0] + t[1]);
;     const f32x2 sav = {sa, sa}, vv = {o.v, o.v};
;     const f32x2 a0 = {o.ka[0], o.ka[1]}, a1 = {o.ka[2], o.ka[3]}, p0 = {o.kp[0], o.kp[1]}, p1 = {o.kp[2], o.kp[3]}, w0 = {o.w[0], o.w[1]}, w1 = {o.w[2], o.w[3]};
;     f32x2 u0 = a0 * sav; u0 = p0 * vv + u0; S0 = S0 * w0 + u0;
;     f32x2 u1 = a1 * sav; u1 = p1 * vv + u1; S1 = S1 * w1 + u1;
;     const f32x2 r0 = {o.rr[0], o.rr[1]}, r1 = {o.rr[2], o.rr[3]};
;     f32x2 y = S0 * r0; y = S1 * r1 + y;
;     *yp = y[0] + y[1];
;     S = (f32x4){S0[0], S0[1], S1[0], S1[1]};
; }
; __device__ __forceinline__ void scan_unit(const Ctx& p, int chain, int rq, LAS unsigned char* lds) {
;     ...
;             for (int t = 0; t < SCH; t += 2) {
;                 scan_load(ob, OP, VP, t + 1);
;                 oa.v = vv[0]; ob.v = vv[1];
;                 scan_step(S, oa, Y + t * 256);
;                 scan_load(oa, OP, VP, (t + 2) & (SCH - 1));
;                 vv = *(const LAS f32x2*)(VP + ((t + 2) & (SCH - 1)));
;                 scan_step(S, ob, Y + (t + 1) * 256);
;             }
	ds_read_b128 v[60:63], v31 offset:7936
	ds_read_b128 v[64:67], v31 offset:8448
	ds_read_b128 v[68:71], v31 offset:7680
	ds_read_b128 v[72:75], v31 offset:8192
	v_mul_f32_e32 v100, v0, v80
	v_mul_f32_e32 v101, v0, v76
	v_fmac_f32_e32 v100, v1, v81
	v_fmac_f32_e32 v101, v1, v77
	v_fmac_f32_e32 v100, v2, v82
	v_fmac_f32_e32 v101, v2, v78
	v_fmac_f32_e32 v100, v3, v83
	v_fmac_f32_e32 v101, v3, v79
	ds_write_b32 v33, v101 offset:3072
	ds_read_b128 v[76:79], v31 offset:8704
	v_mul_f32_e32 v104, v84, v44
	v_mul_f32_e32 v105, v85, v44
	v_add_f32_dpp v100, v100, v100 quad_perm:[1,0,3,2] row_mask:0xf bank_mask:0xf bound_ctrl:1
	v_mul_f32_e32 v106, v86, v44
	v_mul_f32_e32 v107, v87, v44
	v_add_f32_dpp v100, v100, v100 quad_perm:[2,3,0,1] row_mask:0xf bank_mask:0xf bound_ctrl:1
	v_fmac_f32_e32 v104, v0, v88
	v_fmac_f32_e32 v105, v1, v89
	v_add_f32_dpp v100, v100, v100 row_half_mirror row_mask:0xf bank_mask:0xf bound_ctrl:1
	v_fmac_f32_e32 v106, v2, v90
	v_fmac_f32_e32 v107, v3, v91
	v_add_f32_dpp v100, v100, v100 row_mirror row_mask:0xf bank_mask:0xf bound_ctrl:1
	v_fma_f32 v0, -v92, v100, v104
	v_fma_f32 v1, -v93, v100, v105
	v_fma_f32 v2, -v94, v100, v106
	v_fma_f32 v3, -v95, v100, v107
	s_waitcnt lgkmcnt(8)
	ds_read_b128 v[80:83], v31 offset:9216
	ds_read_b128 v[84:87], v31 offset:9728
	ds_read_b128 v[88:91], v31 offset:8960
	ds_read_b128 v[92:95], v31 offset:9472
	v_mul_f32_e32 v100, v0, v120
	v_mul_f32_e32 v101, v0, v96
	v_fmac_f32_e32 v100, v1, v121
	v_fmac_f32_e32 v101, v1, v97
	v_fmac_f32_e32 v100, v2, v122
	v_fmac_f32_e32 v101, v2, v98
	v_fmac_f32_e32 v100, v3, v123
	v_fmac_f32_e32 v101, v3, v99
	ds_write_b32 v33, v101 offset:4096
	ds_read_b128 v[96:99], v31 offset:9984
	v_mul_f32_e32 v104, v124, v45
	v_mul_f32_e32 v105, v125, v45
	v_add_f32_dpp v100, v100, v100 quad_perm:[1,0,3,2] row_mask:0xf bank_mask:0xf bound_ctrl:1
	v_mul_f32_e32 v106, v126, v45
	v_mul_f32_e32 v107, v127, v45
	v_add_f32_dpp v100, v100, v100 quad_perm:[2,3,0,1] row_mask:0xf bank_mask:0xf bound_ctrl:1
	v_fmac_f32_e32 v104, v0, v128
	v_fmac_f32_e32 v105, v1, v129
	v_add_f32_dpp v100, v100, v100 row_half_mirror row_mask:0xf bank_mask:0xf bound_ctrl:1
	v_fmac_f32_e32 v106, v2, v130
	v_fmac_f32_e32 v107, v3, v131
	v_add_f32_dpp v100, v100, v100 row_mirror row_mask:0xf bank_mask:0xf bound_ctrl:1
	v_fma_f32 v0, -v132, v100, v104
	v_fma_f32 v1, -v133, v100, v105
	v_fma_f32 v2, -v134, v100, v106
	v_fma_f32 v3, -v135, v100, v107
	s_waitcnt lgkmcnt(8)
	ds_read_b128 v[120:123], v31 offset:10496
	ds_read_b128 v[124:127], v31 offset:11008
	ds_read_b128 v[128:131], v31 offset:10240
	ds_read_b128 v[132:135], v31 offset:10752
	v_mul_f32_e32 v100, v0, v60
	v_mul_f32_e32 v101, v0, v136
	v_fmac_f32_e32 v100, v1, v61
	v_fmac_f32_e32 v101, v1, v137
	v_fmac_f32_e32 v100, v2, v62
	v_fmac_f32_e32 v101, v2, v138
	v_fmac_f32_e32 v100, v3, v63
	v_fmac_f32_e32 v101, v3, v139
	ds_write_b32 v33, v101 offset:5120
	ds_read_b128 v[136:139], v31 offset:11264
	v_mul_f32_e32 v104, v64, v46
	v_mul_f32_e32 v105, v65, v46
	v_add_f32_dpp v100, v100, v100 quad_perm:[1,0,3,2] row_mask:0xf bank_mask:0xf bound_ctrl:1
	v_mul_f32_e32 v106, v66, v46
	v_mul_f32_e32 v107, v67, v46
	v_add_f32_dpp v100, v100, v100 quad_perm:[2,3,0,1] row_mask:0xf bank_mask:0xf bound_ctrl:1
	v_fmac_f32_e32 v104, v0, v68
	v_fmac_f32_e32 v105, v1, v69
	v_add_f32_dpp v100, v100, v100 row_half_mirror row_mask:0xf bank_mask:0xf bound_ctrl:1
	v_fmac_f32_e32 v106, v2, v70
	v_fmac_f32_e32 v107, v3, v71
	v_add_f32_dpp v100, v100, v100 row_mirror row_mask:0xf bank_mask:0xf bound_ctrl:1
	v_fma_f32 v0, -v72, v100, v104
	v_fma_f32 v1, -v73, v100, v105
	v_fma_f32 v2, -v74, v100, v106
	v_fma_f32 v3, -v75, v100, v107
	s_waitcnt lgkmcnt(8)
	ds_read_b128 v[60:63], v31 offset:11776
	ds_read_b128 v[64:67], v31 offset:12288
	ds_read_b128 v[68:71], v31 offset:11520
	ds_read_b128 v[72:75], v31 offset:12032
	v_mul_f32_e32 v100, v0, v80
	v_mul_f32_e32 v101, v0, v76
	v_fmac_f32_e32 v100, v1, v81
	v_fmac_f32_e32 v101, v1, v77
	v_fmac_f32_e32 v100, v2, v82
	v_fmac_f32_e32 v101, v2, v78
	v_fmac_f32_e32 v100, v3, v83
	v_fmac_f32_e32 v101, v3, v79
	ds_write_b32 v33, v101 offset:6144
	ds_read_b128 v[76:79], v31 offset:12544
	v_mul_f32_e32 v104, v84, v47
	v_mul_f32_e32 v105, v85, v47
	v_add_f32_dpp v100, v100, v100 quad_perm:[1,0,3,2] row_mask:0xf bank_mask:0xf bound_ctrl:1
	v_mul_f32_e32 v106, v86, v47
	v_mul_f32_e32 v107, v87, v47
	v_add_f32_dpp v100, v100, v100 quad_perm:[2,3,0,1] row_mask:0xf bank_mask:0xf bound_ctrl:1
	v_fmac_f32_e32 v104, v0, v88
	v_fmac_f32_e32 v105, v1, v89
	v_add_f32_dpp v100, v100, v100 row_half_mirror row_mask:0xf bank_mask:0xf bound_ctrl:1
	v_fmac_f32_e32 v106, v2, v90
	v_fmac_f32_e32 v107, v3, v91
	v_add_f32_dpp v100, v100, v100 row_mirror row_mask:0xf bank_mask:0xf bound_ctrl:1
	v_fma_f32 v0, -v92, v100, v104
	v_fma_f32 v1, -v93, v100, v105
	v_fma_f32 v2, -v94, v100, v106
	v_fma_f32 v3, -v95, v100, v107
	s_waitcnt lgkmcnt(8)
	ds_read_b128 v[80:83], v31 offset:13056
	ds_read_b128 v[84:87], v31 offset:13568
	ds_read_b128 v[88:91], v31 offset:12800
	ds_read_b128 v[92:95], v31 offset:13312
	v_mul_f32_e32 v100, v0, v120
	v_mul_f32_e32 v101, v0, v96
	v_fmac_f32_e32 v100, v1, v121
	v_fmac_f32_e32 v101, v1, v97
	v_fmac_f32_e32 v100, v2, v122
	v_fmac_f32_e32 v101, v2, v98
	v_fmac_f32_e32 v100, v3, v123
	v_fmac_f32_e32 v101, v3, v99
	ds_write_b32 v33, v101 offset:7168
	ds_read_b128 v[96:99], v31 offset:13824
	v_mul_f32_e32 v104, v124, v48
	v_mul_f32_e32 v105, v125, v48
	v_add_f32_dpp v100, v100, v100 quad_perm:[1,0,3,2] row_mask:0xf bank_mask:0xf bound_ctrl:1
	v_mul_f32_e32 v106, v126, v48
	v_mul_f32_e32 v107, v127, v48
	v_add_f32_dpp v100, v100, v100 quad_perm:[2,3,0,1] row_mask:0xf bank_mask:0xf bound_ctrl:1
	v_fmac_f32_e32 v104, v0, v128
	v_fmac_f32_e32 v105, v1, v129
	v_add_f32_dpp v100, v100, v100 row_half_mirror row_mask:0xf bank_mask:0xf bound_ctrl:1
	v_fmac_f32_e32 v106, v2, v130
	v_fmac_f32_e32 v107, v3, v131
	v_add_f32_dpp v100, v100, v100 row_mirror row_mask:0xf bank_mask:0xf bound_ctrl:1
	v_fma_f32 v0, -v132, v100, v104
	v_fma_f32 v1, -v133, v100, v105
	v_fma_f32 v2, -v134, v100, v106
	v_fma_f32 v3, -v135, v100, v107
	s_waitcnt lgkmcnt(8)
; #define LAS __attribute__((address_space(3)))
; __device__ __forceinline__ float sum16(float x) { x = dpp_add<0xB1>(x); x = dpp_add<0x4E>(x); x = dpp_add<0x141>(x); x = dpp_add<0x140>(x); return x; }
; __device__ __forceinline__ void scan_step(f32x4& S, const ScanOps& o, LAS float* yp) {
;     f32x2 S0 = {S[0], S[1]}, S1 = {S[2], S[3]};
;     const f32x2 k0 = {o.kk[0], o.kk[1]}, k1 = {o.kk[2], o.kk[3]};
;     f32x2 t = S0 * k0; t = S1 * k1 + t;
;     const float sa = -sum16(t[0] + t[1]);
;     const f32x2 sav = {sa, sa}, vv = {o.v, o.v};
;     const f32x2 a0 = {o.ka[0], o.ka[1]}, a1 = {o.ka[2], o.ka[3]}, p0 = {o.kp[0], o.kp[1]}, p1 = {o.kp[2], o.kp[3]}, w0 = {o.w[0], o.w[1]}, w1 = {o.w[2], o.w[3]};
;     f32x2 u0 = a0 * sav; u0 = p0 * vv + u0; S0 = S0 * w0 + u0;
;     f32x2 u1 = a1 * sav; u1 = p1 * vv + u1; S1 = S1 * w1 + u1;
;     const f32x2 r0 = {o.rr[0], o.rr[1]}, r1 = {o.rr[2], o.rr[3]};
;     f32x2 y = S0 * r0; y = S1 * r1 + y;
;     *yp = y[0] + y[1];
;     S = (f32x4){S0[0], S0[1], S1[0], S1[1]};
; }
; __device__ __forceinline__ void scan_unit(const Ctx& p, int chain, int rq, LAS unsigned char* lds) {
;     ...
;             for (int t = 0; t < SCH; t += 2) {
;                 scan_load(ob, OP, VP, t + 1);
;                 oa.v = vv[0]; ob.v = vv[1];
;                 scan_step(S, oa, Y + t * 256);
;                 scan_load(oa, OP, VP, (t + 2) & (SCH - 1));
;                 vv = *(const LAS f32x2*)(VP + ((t + 2) & (SCH - 1)));
;                 scan_step(S, ob, Y + (t + 1) * 256);
;             }
	ds_read_b128 v[120:123], v31 offset:14336
	ds_read_b128 v[124:127], v31 offset:14848
	ds_read_b128 v[128:131], v31 offset:14080
	ds_read_b128 v[132:135], v31 offset:14592
	v_mul_f32_e32 v100, v0, v60
	v_mul_f32_e32 v101, v0, v136
	v_fmac_f32_e32 v100, v1, v61
	v_fmac_f32_e32 v101, v1, v137
	v_fmac_f32_e32 v100, v2, v62
	v_fmac_f32_e32 v101, v2, v138
	v_fmac_f32_e32 v100, v3, v63
	v_fmac_f32_e32 v101, v3, v139
	ds_write_b32 v33, v101 offset:8192
	ds_read_b128 v[136:139], v31 offset:15104
	v_mul_f32_e32 v104, v64, v49
	v_mul_f32_e32 v105, v65, v49
	v_add_f32_dpp v100, v100, v100 quad_perm:[1,0,3,2] row_mask:0xf bank_mask:0xf bound_ctrl:1
	v_mul_f32_e32 v106, v66, v49
	v_mul_f32_e32 v107, v67, v49
	v_add_f32_dpp v100, v100, v100 quad_perm:[2,3,0,1] row_mask:0xf bank_mask:0xf bound_ctrl:1
	v_fmac_f32_e32 v104, v0, v68
	v_fmac_f32_e32 v105, v1, v69
	v_add_f32_dpp v100, v100, v100 row_half_mirror row_mask:0xf bank_mask:0xf bound_ctrl:1
	v_fmac_f32_e32 v106, v2, v70
	v_fmac_f32_e32 v107, v3, v71
	v_add_f32_dpp v100, v100, v100 row_mirror row_mask:0xf bank_mask:0xf bound_ctrl:1
	v_fma_f32 v0, -v72, v100, v104
	v_fma_f32 v1, -v73, v100, v105
	v_fma_f32 v2, -v74, v100, v106
	v_fma_f32 v3, -v75, v100, v107
	s_waitcnt lgkmcnt(8)
	ds_read_b128 v[60:63], v31 offset:15616
	ds_read_b128 v[64:67], v31 offset:16128
	ds_read_b128 v[68:71], v31 offset:15360
	ds_read_b128 v[72:75], v31 offset:15872
	v_mul_f32_e32 v100, v0, v80
	v_mul_f32_e32 v101, v0, v76
	v_fmac_f32_e32 v100, v1, v81
	v_fmac_f32_e32 v101, v1, v77
	v_fmac_f32_e32 v100, v2, v82
	v_fmac_f32_e32 v101, v2, v78
	v_fmac_f32_e32 v100, v3, v83
	v_fmac_f32_e32 v101, v3, v79
	ds_write_b32 v33, v101 offset:9216
	ds_read_b128 v[76:79], v31 offset:16384
	v_mul_f32_e32 v104, v84, v50
	v_mul_f32_e32 v105, v85, v50
	v_add_f32_dpp v100, v100, v100 quad_perm:[1,0,3,2] row_mask:0xf bank_mask:0xf bound_ctrl:1
	v_mul_f32_e32 v106, v86, v50
	v_mul_f32_e32 v107, v87, v50
	v_add_f32_dpp v100, v100, v100 quad_perm:[2,3,0,1] row_mask:0xf bank_mask:0xf bound_ctrl:1
	v_fmac_f32_e32 v104, v0, v88
	v_fmac_f32_e32 v105, v1, v89
	v_add_f32_dpp v100, v100, v100 row_half_mirror row_mask:0xf bank_mask:0xf bound_ctrl:1
	v_fmac_f32_e32 v106, v2, v90
	v_fmac_f32_e32 v107, v3, v91
	v_add_f32_dpp v100, v100, v100 row_mirror row_mask:0xf bank_mask:0xf bound_ctrl:1
	v_fma_f32 v0, -v92, v100, v104
	v_fma_f32 v1, -v93, v100, v105
	v_fma_f32 v2, -v94, v100, v106
	v_fma_f32 v3, -v95, v100, v107
	s_waitcnt lgkmcnt(8)
	ds_read_b128 v[80:83], v31 offset:16896
	ds_read_b128 v[84:87], v31 offset:17408
	ds_read_b128 v[88:91], v31 offset:16640
	ds_read_b128 v[92:95], v31 offset:17152
	v_mul_f32_e32 v100, v0, v120
	v_mul_f32_e32 v101, v0, v96
	v_fmac_f32_e32 v100, v1, v121
	v_fmac_f32_e32 v101, v1, v97
	v_fmac_f32_e32 v100, v2, v122
	v_fmac_f32_e32 v101, v2, v98
	v_fmac_f32_e32 v100, v3, v123
	v_fmac_f32_e32 v101, v3, v99
	ds_write_b32 v33, v101 offset:10240
	ds_read_b128 v[96:99], v31 offset:17664
	v_mul_f32_e32 v104, v124, v51
	v_mul_f32_e32 v105, v125, v51
	v_add_f32_dpp v100, v100, v100 quad_perm:[1,0,3,2] row_mask:0xf bank_mask:0xf bound_ctrl:1
	v_mul_f32_e32 v106, v126, v51
	v_mul_f32_e32 v107, v127, v51
	v_add_f32_dpp v100, v100, v100 quad_perm:[2,3,0,1] row_mask:0xf bank_mask:0xf bound_ctrl:1
	v_fmac_f32_e32 v104, v0, v128
	v_fmac_f32_e32 v105, v1, v129
	v_add_f32_dpp v100, v100, v100 row_half_mirror row_mask:0xf bank_mask:0xf bound_ctrl:1
	v_fmac_f32_e32 v106, v2, v130
	v_fmac_f32_e32 v107, v3, v131
	v_add_f32_dpp v100, v100, v100 row_mirror row_mask:0xf bank_mask:0xf bound_ctrl:1
	v_fma_f32 v0, -v132, v100, v104
	v_fma_f32 v1, -v133, v100, v105
	v_fma_f32 v2, -v134, v100, v106
	v_fma_f32 v3, -v135, v100, v107
	s_waitcnt lgkmcnt(8)
	ds_read_b128 v[120:123], v31 offset:18176
	ds_read_b128 v[124:127], v31 offset:18688
	ds_read_b128 v[128:131], v31 offset:17920
	ds_read_b128 v[132:135], v31 offset:18432
	v_mul_f32_e32 v100, v0, v60
	v_mul_f32_e32 v101, v0, v136
	v_fmac_f32_e32 v100, v1, v61
	v_fmac_f32_e32 v101, v1, v137
	v_fmac_f32_e32 v100, v2, v62
	v_fmac_f32_e32 v101, v2, v138
	v_fmac_f32_e32 v100, v3, v63
	v_fmac_f32_e32 v101, v3, v139
	ds_write_b32 v33, v101 offset:11264
	ds_read_b128 v[136:139], v31 offset:18944
	v_mul_f32_e32 v104, v64, v52
	v_mul_f32_e32 v105, v65, v52
	v_add_f32_dpp v100, v100, v100 quad_perm:[1,0,3,2] row_mask:0xf bank_mask:0xf bound_ctrl:1
	v_mul_f32_e32 v106, v66, v52
	v_mul_f32_e32 v107, v67, v52
	v_add_f32_dpp v100, v100, v100 quad_perm:[2,3,0,1] row_mask:0xf bank_mask:0xf bound_ctrl:1
	v_fmac_f32_e32 v104, v0, v68
	v_fmac_f32_e32 v105, v1, v69
	v_add_f32_dpp v100, v100, v100 row_half_mirror row_mask:0xf bank_mask:0xf bound_ctrl:1
	v_fmac_f32_e32 v106, v2, v70
	v_fmac_f32_e32 v107, v3, v71
	v_add_f32_dpp v100, v100, v100 row_mirror row_mask:0xf bank_mask:0xf bound_ctrl:1
	v_fma_f32 v0, -v72, v100, v104
	v_fma_f32 v1, -v73, v100, v105
	v_fma_f32 v2, -v74, v100, v106
	v_fma_f32 v3, -v75, v100, v107
	s_waitcnt lgkmcnt(8)
; #define LAS __attribute__((address_space(3)))
; __device__ __forceinline__ float sum16(float x) { x = dpp_add<0xB1>(x); x = dpp_add<0x4E>(x); x = dpp_add<0x141>(x); x = dpp_add<0x140>(x); return x; }
; __device__ __forceinline__ void scan_step(f32x4& S, const ScanOps& o, LAS float* yp) {
;     f32x2 S0 = {S[0], S[1]}, S1 = {S[2], S[3]};
;     const f32x2 k0 = {o.kk[0], o.kk[1]}, k1 = {o.kk[2], o.kk[3]};
;     f32x2 t = S0 * k0; t = S1 * k1 + t;
;     const float sa = -sum16(t[0] + t[1]);
;     const f32x2 sav = {sa, sa}, vv = {o.v, o.v};
;     const f32x2 a0 = {o.ka[0], o.ka[1]}, a1 = {o.ka[2], o.ka[3]}, p0 = {o.kp[0], o.kp[1]}, p1 = {o.kp[2], o.kp[3]}, w0 = {o.w[0], o.w[1]}, w1 = {o.w[2], o.w[3]};
;     f32x2 u0 = a0 * sav; u0 = p0 * vv + u0; S0 = S0 * w0 + u0;
;     f32x2 u1 = a1 * sav; u1 = p1 * vv + u1; S1 = S1 * w1 + u1;
;     const f32x2 r0 = {o.rr[0], o.rr[1]}, r1 = {o.rr[2], o.rr[3]};
;     f32x2 y = S0 * r0; y = S1 * r1 + y;
;     *yp = y[0] + y[1];
;     S = (f32x4){S0[0], S0[1], S1[0], S1[1]};
; }
; __device__ __forceinline__ void scan_unit(const Ctx& p, int chain, int rq, LAS unsigned char* lds) {
;     ...
;             for (int t = 0; t < SCH; t += 2) {
;                 scan_load(ob, OP, VP, t + 1);
;                 oa.v = vv[0]; ob.v = vv[1];
;                 scan_step(S, oa, Y + t * 256);
;                 scan_load(oa, OP, VP, (t + 2) & (SCH - 1));
;                 vv = *(const LAS f32x2*)(VP + ((t + 2) & (SCH - 1)));
;                 scan_step(S, ob, Y + (t + 1) * 256);
;             }
;         }
;         __syncthreads();
;         *(f32x4*)sg = S;
	ds_read_b128 v[60:63], v31 offset:19456
	ds_read_b128 v[64:67], v31 offset:19968
	ds_read_b128 v[68:71], v31 offset:19200
	ds_read_b128 v[72:75], v31 offset:19712
	v_mul_f32_e32 v100, v0, v80
	v_mul_f32_e32 v101, v0, v76
	v_fmac_f32_e32 v100, v1, v81
	v_fmac_f32_e32 v101, v1, v77
	v_fmac_f32_e32 v100, v2, v82
	v_fmac_f32_e32 v101, v2, v78
	v_fmac_f32_e32 v100, v3, v83
	v_fmac_f32_e32 v101, v3, v79
	ds_write_b32 v33, v101 offset:12288
	ds_read_b128 v[76:79], v31 offset:20224
	v_mul_f32_e32 v104, v84, v53
	v_mul_f32_e32 v105, v85, v53
	v_add_f32_dpp v100, v100, v100 quad_perm:[1,0,3,2] row_mask:0xf bank_mask:0xf bound_ctrl:1
	v_mul_f32_e32 v106, v86, v53
	v_mul_f32_e32 v107, v87, v53
	v_add_f32_dpp v100, v100, v100 quad_perm:[2,3,0,1] row_mask:0xf bank_mask:0xf bound_ctrl:1
	v_fmac_f32_e32 v104, v0, v88
	v_fmac_f32_e32 v105, v1, v89
	v_add_f32_dpp v100, v100, v100 row_half_mirror row_mask:0xf bank_mask:0xf bound_ctrl:1
	v_fmac_f32_e32 v106, v2, v90
	v_fmac_f32_e32 v107, v3, v91
	v_add_f32_dpp v100, v100, v100 row_mirror row_mask:0xf bank_mask:0xf bound_ctrl:1
	v_fma_f32 v0, -v92, v100, v104
	v_fma_f32 v1, -v93, v100, v105
	v_fma_f32 v2, -v94, v100, v106
	v_fma_f32 v3, -v95, v100, v107
	s_waitcnt lgkmcnt(8)
	v_mul_f32_e32 v100, v0, v120
	v_mul_f32_e32 v101, v0, v96
	v_fmac_f32_e32 v100, v1, v121
	v_fmac_f32_e32 v101, v1, v97
	v_fmac_f32_e32 v100, v2, v122
	v_fmac_f32_e32 v101, v2, v98
	v_fmac_f32_e32 v100, v3, v123
	v_fmac_f32_e32 v101, v3, v99
	ds_write_b32 v33, v101 offset:13312
	v_mul_f32_e32 v104, v124, v54
	v_mul_f32_e32 v105, v125, v54
	v_add_f32_dpp v100, v100, v100 quad_perm:[1,0,3,2] row_mask:0xf bank_mask:0xf bound_ctrl:1
	v_mul_f32_e32 v106, v126, v54
	v_mul_f32_e32 v107, v127, v54
	v_add_f32_dpp v100, v100, v100 quad_perm:[2,3,0,1] row_mask:0xf bank_mask:0xf bound_ctrl:1
	v_fmac_f32_e32 v104, v0, v128
	v_fmac_f32_e32 v105, v1, v129
	v_add_f32_dpp v100, v100, v100 row_half_mirror row_mask:0xf bank_mask:0xf bound_ctrl:1
	v_fmac_f32_e32 v106, v2, v130
	v_fmac_f32_e32 v107, v3, v131
	v_add_f32_dpp v100, v100, v100 row_mirror row_mask:0xf bank_mask:0xf bound_ctrl:1
	v_fma_f32 v0, -v132, v100, v104
	v_fma_f32 v1, -v133, v100, v105
	v_fma_f32 v2, -v134, v100, v106
	v_fma_f32 v3, -v135, v100, v107
	s_waitcnt lgkmcnt(3)
	v_mul_f32_e32 v100, v0, v60
	v_mul_f32_e32 v101, v0, v136
	v_fmac_f32_e32 v100, v1, v61
	v_fmac_f32_e32 v101, v1, v137
	v_fmac_f32_e32 v100, v2, v62
	v_fmac_f32_e32 v101, v2, v138
	v_fmac_f32_e32 v100, v3, v63
	v_fmac_f32_e32 v101, v3, v139
	ds_write_b32 v33, v101 offset:14336
	v_mul_f32_e32 v104, v64, v55
	v_mul_f32_e32 v105, v65, v55
	v_add_f32_dpp v100, v100, v100 quad_perm:[1,0,3,2] row_mask:0xf bank_mask:0xf bound_ctrl:1
	v_mul_f32_e32 v106, v66, v55
	v_mul_f32_e32 v107, v67, v55
	v_add_f32_dpp v100, v100, v100 quad_perm:[2,3,0,1] row_mask:0xf bank_mask:0xf bound_ctrl:1
	v_fmac_f32_e32 v104, v0, v68
	v_fmac_f32_e32 v105, v1, v69
	v_add_f32_dpp v100, v100, v100 row_half_mirror row_mask:0xf bank_mask:0xf bound_ctrl:1
	v_fmac_f32_e32 v106, v2, v70
	v_fmac_f32_e32 v107, v3, v71
	v_add_f32_dpp v100, v100, v100 row_mirror row_mask:0xf bank_mask:0xf bound_ctrl:1
	v_fma_f32 v0, -v72, v100, v104
	v_fma_f32 v1, -v73, v100, v105
	v_fma_f32 v2, -v74, v100, v106
	v_fma_f32 v3, -v75, v100, v107
	s_waitcnt lgkmcnt(2)
	v_mul_f32_e32 v101, v0, v76
	v_fmac_f32_e32 v101, v1, v77
	v_fmac_f32_e32 v101, v2, v78
	v_fmac_f32_e32 v101, v3, v79
	ds_write_b32 v33, v101 offset:15360
	s_add_i32 s10, s10, 1
	s_cmpk_eq_i32 s10, 0x100
	s_cbranch_scc0 .LBB0_1714
	s_setprio 0
	s_lshl_b32 s8, s28, 12
	v_lshl_or_b32 v4, v27, 8, s8
	v_mov_b32_e32 v5, 0
	v_lshl_add_u64 v[6:7], s[2:3], 0, v[4:5]
	v_lshlrev_b32_e32 v4, 2, v26
	v_lshl_add_u64 v[4:5], v[6:7], 0, v[4:5]
	v_add_co_u32_e32 v4, vcc, 0x8080000, v4
	s_mov_b64 s[2:3], 0
	s_nop 0
	v_addc_co_u32_e32 v5, vcc, 0, v5, vcc
	s_waitcnt lgkmcnt(0)
	s_barrier
	global_store_dwordx4 v[4:5], v[0:3], off
